# NA softmax: scale+bias, max-subtract and row-sum done with packed f32 ops (v_pk_fma_f32 / v_pk_add_f32) on register pairs; bias registers re-homed to aligned pairs; 48 fewer VALU per trip
# speedup vs baseline: 1.0076x; 1.0076x over previous
.LBB0_703:
	v_sub_u32_e64 v0, s0, 4 clamp
	v_ashrrev_i32_e32 v57, 3, v152
	v_readfirstlane_b32 s0, v0
	v_sub_u32_e64 v0, v61, 8 clamp
	v_lshrrev_b32_e32 v5, 2, v57
	v_min_u32_e32 v2, 48, v0
	v_and_b32_e32 v3, 7, v152
	v_bfe_u32 v0, v57, 1, 1
	v_and_b32_e32 v5, 6, v5
	v_bitop3_b32 v0, v0, v3, v5 bitop3:0x36
	v_lshl_add_u32 v65, v0, 4, 0
	v_lshlrev_b32_e32 v0, 3, v152
	v_and_b32_e32 v64, 56, v0
	v_lshlrev_b32_e32 v0, 4, v152
	v_and_b32_e32 v0, 0x3f0, v0
	v_lshrrev_b32_e32 v5, 5, v152
	s_and_b64 s[38:39], s[40:41], exec
	v_lshl_add_u64 v[66:67], s[16:17], 0, v[0:1]
	v_bfe_u32 v0, v152, 4, 1
	v_and_b32_e32 v5, 6, v5
	s_cselect_b32 s1, 24, 0xf8
	v_bitop3_b32 v0, v0, v3, v5 bitop3:0x36
	s_min_u32 s66, s0, s1
	v_readlane_b32 s0, v255, 21
	v_lshl_add_u32 v83, v0, 4, 0
	v_lshlrev_b32_e32 v0, 1, v199
	v_add_u32_e32 v88, s82, v150
	v_lshl_add_u32 v4, v193, 2, s0
	s_add_i32 s10, 0, 0x12000
	s_add_i32 s20, s59, -1
	s_and_b32 s83, s25, 4
	v_and_b32_e32 v85, 24, v0
	s_and_b32 s0, s25, -4
	v_add_u32_e32 v0, 16, v2
	v_or_b32_e32 v120, 4, v88
	s_cmp_eq_u32 s0, 4
	v_cmp_ge_i32_e32 vcc, v120, v2
	v_cmp_lt_i32_e64 s[40:41], v120, v0
	s_cselect_b64 s[80:81], -1, 0
	s_and_b64 s[40:41], vcc, s[40:41]
	v_cmp_ge_i32_e32 vcc, v88, v2
	v_cmp_lt_i32_e64 s[42:43], v88, v0
	v_or_b32_e32 v121, 1, v88
	s_and_b64 s[42:43], vcc, s[42:43]
	v_cmp_ge_i32_e32 vcc, v121, v2
	v_cmp_lt_i32_e64 s[44:45], v121, v0
	v_or_b32_e32 v122, 2, v88
	s_and_b64 s[44:45], vcc, s[44:45]
	v_cmp_ge_i32_e32 vcc, v122, v2
	v_cmp_lt_i32_e64 s[46:47], v122, v0
	v_or_b32_e32 v123, 3, v88
	s_and_b64 s[46:47], vcc, s[46:47]
	v_cmp_ge_i32_e32 vcc, v123, v2
	v_cmp_lt_i32_e64 s[48:49], v123, v0
	v_or_b32_e32 v124, 5, v88
	s_and_b64 s[48:49], vcc, s[48:49]
	v_cmp_ge_i32_e32 vcc, v124, v2
	v_cmp_lt_i32_e64 s[50:51], v124, v0
	v_or_b32_e32 v125, 6, v88
	v_or_b32_e32 v126, 7, v88
	v_lshl_add_u32 v60, v3, 4, s10
	v_and_b32_e32 v3, -16, v193
	s_and_b64 s[50:51], vcc, s[50:51]
	v_cmp_ge_i32_e32 vcc, v125, v2
	v_cmp_lt_i32_e64 s[52:53], v125, v0
	v_cmp_lt_i32_e64 s[54:55], v126, v0
	v_mul_u32_u24_e32 v0, 0x410, v199
	s_movk_i32 s35, 0x410
	s_mul_i32 s26, s58, 0xa00
	v_add_u32_e32 v5, 0x200, v152
	v_add_u32_e32 v6, 0x400, v152
	v_add_u32_e32 v7, 0x600, v152
	v_add_u32_e32 v8, 0x800, v152
	v_add_u32_e32 v9, 0xa00, v152
	v_add_u32_e32 v10, 0xc00, v152
	v_add_u32_e32 v11, 0xe00, v152
	s_and_b64 s[52:53], vcc, s[52:53]
	v_cmp_ge_i32_e32 vcc, v126, v2
	v_add3_u32 v127, s10, v3, v0
	v_mov_b32_e32 v2, v1
	v_mov_b32_e32 v3, v1
	v_mad_u64_u32 v[62:63], s[38:39], v57, s35, v[60:61]
	v_ashrrev_i32_e32 v89, 6, v152
	v_ashrrev_i32_e32 v90, 3, v5
	v_ashrrev_i32_e32 v91, 6, v5
	v_ashrrev_i32_e32 v92, 3, v6
	v_ashrrev_i32_e32 v93, 6, v6
	v_ashrrev_i32_e32 v94, 3, v7
	v_ashrrev_i32_e32 v95, 6, v7
	v_ashrrev_i32_e32 v96, 3, v8
	v_ashrrev_i32_e32 v97, 6, v8
	v_ashrrev_i32_e32 v98, 3, v9
	v_ashrrev_i32_e32 v99, 6, v9
	v_ashrrev_i32_e32 v100, 3, v10
	v_ashrrev_i32_e32 v101, 6, v10
	v_ashrrev_i32_e32 v102, 3, v11
	v_ashrrev_i32_e32 v103, 6, v11
	v_lshrrev_b32_e32 v106, 9, v5
	v_lshrrev_b32_e32 v108, 9, v6
	v_lshrrev_b32_e32 v110, 9, v7
	v_lshrrev_b32_e32 v112, 9, v8
	v_lshrrev_b32_e32 v114, 9, v9
	v_lshrrev_b32_e32 v116, 9, v10
	v_lshrrev_b32_e32 v118, 9, v11
	v_mov_b32_e32 v0, v1
	v_add_u32_e32 v128, s26, v4
	v_mov_b64_e32 v[6:7], v[2:3]
	v_mov_b64_e32 v[10:11], v[2:3]
	s_mov_b32 s1, 2
	v_lshrrev_b32_e32 v63, 3, v152
	v_bfe_u32 v82, v152, 3, 6
	s_mov_b32 s38, -1
	v_add_u32_e32 v84, 0x200, v57
	v_and_b32_e32 v86, 3, v193
	v_add_u32_e32 v87, 4, v198
	v_lshrrev_b32_e32 v104, 9, v152
	v_mul_lo_u32 v105, v89, s35
	v_mul_lo_u32 v107, v91, s35
	v_mul_lo_u32 v109, v93, s35
	v_mul_lo_u32 v111, v95, s35
	v_mul_lo_u32 v113, v97, s35
	v_mul_lo_u32 v115, v99, s35
	v_mul_lo_u32 v117, v101, s35
	v_mul_lo_u32 v119, v103, s35
	s_and_b64 s[54:55], vcc, s[54:55]
	v_mov_b32_e32 v129, 0
	v_mov_b32_e32 v130, 0
	v_mov_b32_e32 v131, 0
	v_mov_b32_e32 v132, 0
	v_mov_b32_e32 v133, 0
	v_mov_b32_e32 v134, 0
	v_mov_b32_e32 v135, 0
	v_mov_b32_e32 v136, 0
	v_mov_b32_e32 v137, 0
	v_mov_b32_e32 v138, 0
	v_mov_b32_e32 v139, 0
	v_mov_b32_e32 v140, 0
	v_mov_b32_e32 v141, 0
	v_mov_b32_e32 v142, 0
	v_mov_b32_e32 v143, 0
	v_mov_b32_e32 v144, 0
	v_mov_b32_e32 v145, 0
	v_mov_b32_e32 v146, 0
	v_mov_b32_e32 v147, 0
	v_mov_b32_e32 v148, 0
	v_mov_b32_e32 v149, 0
	v_mov_b32_e32 v152, 0
	v_mov_b32_e32 v154, 0
	v_mov_b32_e32 v155, 0
	v_mov_b32_e32 v156, 0
	v_mov_b32_e32 v157, 0
	v_mov_b32_e32 v158, 0
	v_mov_b32_e32 v159, 0
	v_mov_b32_e32 v160, 0
	v_mov_b32_e32 v161, 0
	v_mov_b32_e32 v162, 0
	v_mov_b32_e32 v163, 0
	v_mov_b64_e32 v[4:5], v[0:1]
	v_mov_b64_e32 v[8:9], v[0:1]
	s_waitcnt vmcnt(0)
	v_add_u32_e32 v250, s82, v85
	v_or_b32_e32 v251, v250, v86
	v_lshrrev_b32_e32 v250, 2, v250
	v_lshlrev_b32_e32 v252, 7, v251
	v_bfe_u32 v251, v251, 1, 1
	v_and_b32_e32 v250, 6, v250
	v_bitop3_b32 v248, v251, v198, v250 bitop3:0x36
	v_bitop3_b32 v249, v251, v87, v250 bitop3:0x36
	v_lshl_add_u32 v248, v248, 4, v252
	v_lshl_add_u32 v249, v249, 4, v252
	s_mov_b32 s100, 0x3e38aa3b
	v_mov_b32_e32 v224, 0
	v_mov_b32_e32 v225, 0
	s_branch .LBB0_705

.LBB0_716:
	s_add_i32 s10, s91, s83
	s_lshl_b32 s10, s10, 6
	s_and_b32 s26, s10, 0x1c0
	s_or_b32 vcc_hi, s26, s82
	s_lshl_b32 s26, s26, 7
	v_add_u32_e32 v250, s26, v248
	v_add_u32_e32 v251, s26, v249
	s_add_i32 s26, s10, 64
	s_and_b32 s26, s26, 0x1c0
	s_or_b32 s35, s26, s82
	ds_read_b128 v[28:31], v250
	ds_read_b128 v[32:35], v251
	ds_read_b128 v[36:39], v250 offset:512
	ds_read_b128 v[40:43], v251 offset:512
	s_lshl_b32 s26, s26, 7
	v_add_u32_e32 v252, s26, v248
	v_add_u32_e32 v253, s26, v249
	s_add_i32 s26, s10, 0x80
	s_and_b32 s26, s26, 0x1c0
	s_or_b32 vcc_lo, s26, s82
	ds_read_b128 v[44:47], v252
	ds_read_b128 v[164:167], v253
	ds_read_b128 v[168:171], v252 offset:512
	ds_read_b128 v[172:175], v253 offset:512
	s_lshl_b32 s26, s26, 7
	v_add_u32_e32 v250, s26, v248
	v_add_u32_e32 v251, s26, v249
	s_addk_i32 s10, 0xc0
	s_and_b32 s10, s10, 0x1c0
	ds_read_b128 v[176:179], v250
	ds_read_b128 v[180:183], v251
	ds_read_b128 v[200:203], v250 offset:512
	ds_read_b128 v[204:207], v251 offset:512
	s_lshl_b32 s26, s10, 7
	s_or_b32 s10, s10, s82
	v_add_u32_e32 v252, s26, v248
	v_add_u32_e32 v253, s26, v249
	ds_read_b128 v[208:211], v252
	ds_read_b128 v[212:215], v253
	ds_read_b128 v[216:219], v252 offset:512
	ds_read_b128 v[220:223], v253 offset:512
	s_setprio 1
	s_waitcnt lgkmcnt(14)
	v_mfma_f32_16x16x32_bf16 v[28:31], v[28:31], v[24:27], 0
	v_mfma_f32_16x16x32_bf16 v[52:55], v[32:35], v[20:23], v[28:31]
	s_waitcnt lgkmcnt(13)
	v_mfma_f32_16x16x32_bf16 v[28:31], v[36:39], v[24:27], 0
	s_waitcnt lgkmcnt(12)
	v_mfma_f32_16x16x32_bf16 v[48:51], v[40:43], v[20:23], v[28:31]
	s_waitcnt lgkmcnt(11)
	v_mfma_f32_16x16x32_bf16 v[28:31], v[44:47], v[24:27], 0
	s_waitcnt lgkmcnt(10)
	v_mfma_f32_16x16x32_bf16 v[44:47], v[164:167], v[20:23], v[28:31]
	s_waitcnt lgkmcnt(9)
	v_mfma_f32_16x16x32_bf16 v[28:31], v[168:171], v[24:27], 0
	s_waitcnt lgkmcnt(8)
	v_mfma_f32_16x16x32_bf16 v[40:43], v[172:175], v[20:23], v[28:31]
	s_waitcnt lgkmcnt(7)
	v_mfma_f32_16x16x32_bf16 v[28:31], v[176:179], v[24:27], 0
	s_waitcnt lgkmcnt(6)
	v_mfma_f32_16x16x32_bf16 v[36:39], v[180:183], v[20:23], v[28:31]
	s_waitcnt lgkmcnt(5)
	v_mfma_f32_16x16x32_bf16 v[28:31], v[200:203], v[24:27], 0
	s_waitcnt lgkmcnt(4)
	v_mfma_f32_16x16x32_bf16 v[32:35], v[204:207], v[20:23], v[28:31]
	s_waitcnt lgkmcnt(3)
	v_mfma_f32_16x16x32_bf16 v[28:31], v[208:211], v[24:27], 0
	s_waitcnt lgkmcnt(1)
	v_mfma_f32_16x16x32_bf16 v[24:27], v[216:219], v[24:27], 0
	v_mfma_f32_16x16x32_bf16 v[28:31], v[212:215], v[20:23], v[28:31]
	s_waitcnt lgkmcnt(0)
	v_mfma_f32_16x16x32_bf16 v[20:23], v[220:223], v[20:23], v[24:27]
	s_setprio 0
	s_lshl_b32 s26, s90, 6
	s_or_b32 s39, s26, 16
	s_sub_i32 s67, s39, s70
	s_add_i32 s67, s67, s91
	s_cmp_eq_u32 s67, s38
	s_cbranch_scc1 .LBB0_718
	s_sub_i32 s39, s0, s70
	s_add_i32 s39, s39, s91
	s_mul_i32 s39, s39, 31
	v_sub_u32_e32 v0, s39, v61
	s_mulk_i32 s90, 0x744
	v_add_u32_e32 v24, 0xe8, v0
	s_add_i32 s38, s90, 0
	v_add_u32_e32 v25, v24, v88
	v_add_u32_e32 v26, v24, v121
	v_add_u32_e32 v27, v24, v122
	v_add_u32_e32 v129, v24, v123
	v_add_u32_e32 v130, v24, v120
	v_add_u32_e32 v131, v24, v124
	v_add_u32_e32 v132, v24, v125
	v_add_u32_e32 v24, v24, v126
	s_add_i32 s38, s38, 0x22400
	v_cndmask_b32_e64 v129, 0, v129, s[48:49]
	v_cndmask_b32_e64 v130, 0, v130, s[40:41]
	v_cndmask_b32_e64 v131, 0, v131, s[50:51]
	v_cndmask_b32_e64 v132, 0, v132, s[52:53]
	v_cndmask_b32_e64 v24, 0, v24, s[54:55]
	v_cndmask_b32_e64 v25, 0, v25, s[42:43]
	v_cndmask_b32_e64 v26, 0, v26, s[44:45]
	v_cndmask_b32_e64 v27, 0, v27, s[46:47]
	v_lshl_add_u32 v129, v129, 2, s38
	v_lshl_add_u32 v130, v130, 2, s38
	v_lshl_add_u32 v131, v131, 2, s38
	v_lshl_add_u32 v132, v132, 2, s38
	v_lshl_add_u32 v24, v24, 2, s38
	v_lshl_add_u32 v25, v25, 2, s38
	v_lshl_add_u32 v26, v26, 2, s38
	v_lshl_add_u32 v27, v27, 2, s38
	ds_read_b32 v136, v24
	ds_read_b32 v135, v132
	ds_read_b32 v134, v131
	ds_read_b32 v133, v130
	ds_read_b32 v132, v129
	ds_read_b32 v131, v27
	ds_read_b32 v130, v26
	ds_read_b32 v129, v25
	v_add_u32_e32 v24, 0x107, v0
	v_add_u32_e32 v25, v24, v88
	v_add_u32_e32 v26, v24, v121
	v_add_u32_e32 v27, v24, v122
	v_add_u32_e32 v137, v24, v123
	v_add_u32_e32 v138, v24, v120
	v_add_u32_e32 v139, v24, v124
	v_add_u32_e32 v140, v24, v125
	v_add_u32_e32 v24, v24, v126
	v_cndmask_b32_e64 v137, 0, v137, s[48:49]
	v_cndmask_b32_e64 v138, 0, v138, s[40:41]
	v_cndmask_b32_e64 v139, 0, v139, s[50:51]
	v_cndmask_b32_e64 v140, 0, v140, s[52:53]
	v_cndmask_b32_e64 v24, 0, v24, s[54:55]
	v_cndmask_b32_e64 v25, 0, v25, s[42:43]
	v_cndmask_b32_e64 v26, 0, v26, s[44:45]
	v_cndmask_b32_e64 v27, 0, v27, s[46:47]
	v_lshl_add_u32 v137, v137, 2, s38
	v_lshl_add_u32 v138, v138, 2, s38
	v_lshl_add_u32 v139, v139, 2, s38
	v_lshl_add_u32 v140, v140, 2, s38
	v_lshl_add_u32 v24, v24, 2, s38
	s_waitcnt lgkmcnt(0)
	v_lshl_add_u32 v25, v25, 2, s38
	v_lshl_add_u32 v26, v26, 2, s38
	v_lshl_add_u32 v27, v27, 2, s38
	ds_read_b32 v144, v24
	ds_read_b32 v143, v140
	ds_read_b32 v142, v139
	ds_read_b32 v141, v138
	ds_read_b32 v140, v137
	ds_read_b32 v139, v27
	ds_read_b32 v138, v26
	ds_read_b32 v137, v25
	v_add_u32_e32 v24, 0x126, v0
	v_add_u32_e32 v25, v24, v88
	v_add_u32_e32 v26, v24, v121
	v_add_u32_e32 v27, v24, v122
	v_add_u32_e32 v145, v24, v123
	v_add_u32_e32 v146, v24, v120
	v_add_u32_e32 v147, v24, v124
	v_add_u32_e32 v148, v24, v125
	v_add_u32_e32 v24, v24, v126
	v_cndmask_b32_e64 v145, 0, v145, s[48:49]
	v_cndmask_b32_e64 v146, 0, v146, s[40:41]
	v_cndmask_b32_e64 v147, 0, v147, s[50:51]
	v_cndmask_b32_e64 v148, 0, v148, s[52:53]
	v_cndmask_b32_e64 v24, 0, v24, s[54:55]
	v_cndmask_b32_e64 v25, 0, v25, s[42:43]
	v_cndmask_b32_e64 v26, 0, v26, s[44:45]
	v_cndmask_b32_e64 v27, 0, v27, s[46:47]
	v_lshl_add_u32 v145, v145, 2, s38
	v_lshl_add_u32 v146, v146, 2, s38
	v_lshl_add_u32 v147, v147, 2, s38
	v_lshl_add_u32 v148, v148, 2, s38
	v_lshl_add_u32 v24, v24, 2, s38
	s_waitcnt lgkmcnt(0)
	v_lshl_add_u32 v25, v25, 2, s38
	v_lshl_add_u32 v26, v26, 2, s38
	v_lshl_add_u32 v27, v27, 2, s38
	ds_read_b32 v155, v24
	ds_read_b32 v154, v148
	ds_read_b32 v152, v147
	ds_read_b32 v149, v146
	ds_read_b32 v148, v145
	ds_read_b32 v147, v27
	ds_read_b32 v146, v26
	ds_read_b32 v145, v25
	v_add_u32_e32 v0, 0x145, v0
	v_add_u32_e32 v24, v0, v88
	v_add_u32_e32 v25, v0, v121
	v_add_u32_e32 v26, v0, v122
	v_add_u32_e32 v27, v0, v123
	v_add_u32_e32 v156, v0, v120
	v_add_u32_e32 v157, v0, v124
	v_add_u32_e32 v158, v0, v125
	v_add_u32_e32 v0, v0, v126
	v_cndmask_b32_e64 v156, 0, v156, s[40:41]
	v_cndmask_b32_e64 v157, 0, v157, s[50:51]
	v_cndmask_b32_e64 v158, 0, v158, s[52:53]
	v_cndmask_b32_e64 v0, 0, v0, s[54:55]
	v_cndmask_b32_e64 v24, 0, v24, s[42:43]
	v_cndmask_b32_e64 v25, 0, v25, s[44:45]
	v_cndmask_b32_e64 v26, 0, v26, s[46:47]
	v_cndmask_b32_e64 v27, 0, v27, s[48:49]
	v_lshl_add_u32 v156, v156, 2, s38
	v_lshl_add_u32 v157, v157, 2, s38
	v_lshl_add_u32 v158, v158, 2, s38
	v_lshl_add_u32 v0, v0, 2, s38
	s_waitcnt lgkmcnt(0)
	v_lshl_add_u32 v24, v24, 2, s38
	v_lshl_add_u32 v25, v25, 2, s38
	v_lshl_add_u32 v26, v26, 2, s38
	v_lshl_add_u32 v27, v27, 2, s38
	ds_read_b32 v163, v0
	ds_read_b32 v162, v158
	ds_read_b32 v161, v157
	ds_read_b32 v160, v156
	ds_read_b32 v159, v27
	ds_read_b32 v158, v26
	ds_read_b32 v157, v25
	ds_read_b32 v156, v24
	s_mov_b32 s38, s67
	s_waitcnt lgkmcnt(0)
	v_cndmask_b32_e64 v224, v238, v149, s[40:41]
	v_cndmask_b32_e64 v225, v238, v152, s[50:51]
	v_cndmask_b32_e64 v149, v238, v148, s[48:49]
	v_cndmask_b32_e64 v148, v238, v147, s[46:47]
	v_cndmask_b32_e64 v147, v238, v146, s[44:45]
	v_cndmask_b32_e64 v146, v238, v145, s[42:43]
	v_cndmask_b32_e64 v145, v238, v144, s[54:55]
	v_cndmask_b32_e64 v144, v238, v143, s[52:53]
	v_cndmask_b32_e64 v143, v238, v142, s[50:51]
	v_cndmask_b32_e64 v142, v238, v141, s[40:41]
	v_cndmask_b32_e64 v141, v238, v140, s[48:49]
	v_cndmask_b32_e64 v140, v238, v139, s[46:47]
	v_cndmask_b32_e64 v139, v238, v138, s[44:45]
	v_cndmask_b32_e64 v138, v238, v137, s[42:43]
	v_cndmask_b32_e64 v137, v238, v136, s[54:55]
	v_cndmask_b32_e64 v136, v238, v135, s[52:53]
	v_cndmask_b32_e64 v135, v238, v134, s[50:51]
	v_cndmask_b32_e64 v134, v238, v133, s[40:41]
	v_cndmask_b32_e64 v133, v238, v132, s[48:49]
	v_cndmask_b32_e64 v132, v238, v131, s[46:47]
	v_cndmask_b32_e64 v131, v238, v130, s[44:45]
	v_cndmask_b32_e64 v130, v238, v129, s[42:43]
	v_cndmask_b32_e64 v154, v238, v154, s[52:53]
	v_cndmask_b32_e64 v155, v238, v155, s[54:55]
	v_cndmask_b32_e64 v156, v238, v156, s[42:43]
	v_cndmask_b32_e64 v157, v238, v157, s[44:45]
	v_cndmask_b32_e64 v158, v238, v158, s[46:47]
	v_cndmask_b32_e64 v159, v238, v159, s[48:49]
	v_cndmask_b32_e64 v160, v238, v160, s[40:41]
	v_cndmask_b32_e64 v161, v238, v161, s[50:51]
	v_cndmask_b32_e64 v162, v238, v162, s[52:53]
	v_cndmask_b32_e64 v163, v238, v163, s[54:55]
.LBB0_718:
	s_mov_b32 s39, 0xff800000
	v_pk_fma_f32 v[24:25], v[52:53], s[100:101], v[130:131] op_sel_hi:[1,0,1]
	v_pk_fma_f32 v[26:27], v[54:55], s[100:101], v[132:133] op_sel_hi:[1,0,1]
	v_max3_f32 v0, v24, s39, v25
	v_pk_fma_f32 v[48:49], v[48:49], s[100:101], v[134:135] op_sel_hi:[1,0,1]
	v_max3_f32 v0, v0, v26, v27
	v_pk_fma_f32 v[50:51], v[50:51], s[100:101], v[136:137] op_sel_hi:[1,0,1]
	v_max3_f32 v0, v0, v48, v49
	v_pk_fma_f32 v[44:45], v[44:45], s[100:101], v[138:139] op_sel_hi:[1,0,1]
	v_max3_f32 v0, v0, v50, v51
	v_pk_fma_f32 v[46:47], v[46:47], s[100:101], v[140:141] op_sel_hi:[1,0,1]
	v_max3_f32 v0, v0, v44, v45
	v_pk_fma_f32 v[40:41], v[40:41], s[100:101], v[142:143] op_sel_hi:[1,0,1]
	v_max3_f32 v0, v0, v46, v47
	v_pk_fma_f32 v[42:43], v[42:43], s[100:101], v[144:145] op_sel_hi:[1,0,1]
	v_max3_f32 v0, v0, v40, v41
	v_pk_fma_f32 v[36:37], v[36:37], s[100:101], v[146:147] op_sel_hi:[1,0,1]
	v_max3_f32 v0, v0, v42, v43
	v_pk_fma_f32 v[38:39], v[38:39], s[100:101], v[148:149] op_sel_hi:[1,0,1]
	v_max3_f32 v0, v0, v36, v37
	v_pk_fma_f32 v[32:33], v[32:33], s[100:101], v[224:225] op_sel_hi:[1,0,1]
	v_max3_f32 v0, v0, v38, v39
	v_pk_fma_f32 v[34:35], v[34:35], s[100:101], v[154:155] op_sel_hi:[1,0,1]
	v_max3_f32 v0, v0, v32, v33
	v_pk_fma_f32 v[28:29], v[28:29], s[100:101], v[156:157] op_sel_hi:[1,0,1]
	v_max3_f32 v0, v0, v34, v35
	v_pk_fma_f32 v[30:31], v[30:31], s[100:101], v[158:159] op_sel_hi:[1,0,1]
	v_max3_f32 v0, v0, v28, v29
	v_pk_fma_f32 v[20:21], v[20:21], s[100:101], v[160:161] op_sel_hi:[1,0,1]
	v_max3_f32 v0, v0, v30, v31
	v_pk_fma_f32 v[22:23], v[22:23], s[100:101], v[162:163] op_sel_hi:[1,0,1]
	v_max3_f32 v0, v0, v20, v21
	v_max3_f32 v0, v0, v22, v23
	v_mov_b32_e32 v52, v0
	s_nop 1
	v_permlane16_swap_b32_e32 v0, v52
	v_max_f32_e32 v52, v52, v52
	v_max_f32_e32 v0, v0, v0
	v_max_f32_e32 v0, v0, v52
	v_mov_b32_e32 v52, v0
	s_nop 1
	v_permlane32_swap_b32_e32 v0, v52
	v_max_f32_e32 v52, v52, v52
	v_max_f32_e32 v0, v0, v0
	v_max_f32_e32 v0, v0, v52
	v_pk_add_f32 v[24:25], v[24:25], v[0:1] op_sel_hi:[1,0] neg_lo:[0,1] neg_hi:[0,1]
	v_pk_add_f32 v[26:27], v[26:27], v[0:1] op_sel_hi:[1,0] neg_lo:[0,1] neg_hi:[0,1]
	v_pk_add_f32 v[48:49], v[48:49], v[0:1] op_sel_hi:[1,0] neg_lo:[0,1] neg_hi:[0,1]
	v_exp_f32_e32 v52, v24
	v_exp_f32_e32 v53, v25
	v_pk_add_f32 v[50:51], v[50:51], v[0:1] op_sel_hi:[1,0] neg_lo:[0,1] neg_hi:[0,1]
	v_exp_f32_e32 v54, v26
	v_exp_f32_e32 v55, v27
	v_pk_add_f32 v[44:45], v[44:45], v[0:1] op_sel_hi:[1,0] neg_lo:[0,1] neg_hi:[0,1]
	v_exp_f32_e32 v164, v48
	v_exp_f32_e32 v165, v49
	v_pk_add_f32 v[24:25], v[52:53], v[54:55]
	v_pk_add_f32 v[46:47], v[46:47], v[0:1] op_sel_hi:[1,0] neg_lo:[0,1] neg_hi:[0,1]
	v_exp_f32_e32 v166, v50
	v_exp_f32_e32 v167, v51
	v_pk_add_f32 v[24:25], v[24:25], v[164:165]
	v_pk_add_f32 v[40:41], v[40:41], v[0:1] op_sel_hi:[1,0] neg_lo:[0,1] neg_hi:[0,1]
	v_exp_f32_e32 v168, v44
	v_exp_f32_e32 v169, v45
	v_pk_add_f32 v[24:25], v[24:25], v[166:167]
	v_pk_add_f32 v[42:43], v[42:43], v[0:1] op_sel_hi:[1,0] neg_lo:[0,1] neg_hi:[0,1]
	v_exp_f32_e32 v170, v46
	v_exp_f32_e32 v171, v47
	v_pk_add_f32 v[24:25], v[24:25], v[168:169]
	v_pk_add_f32 v[36:37], v[36:37], v[0:1] op_sel_hi:[1,0] neg_lo:[0,1] neg_hi:[0,1]
	v_exp_f32_e32 v172, v40
	v_exp_f32_e32 v173, v41
	v_pk_add_f32 v[24:25], v[24:25], v[170:171]
	v_pk_add_f32 v[38:39], v[38:39], v[0:1] op_sel_hi:[1,0] neg_lo:[0,1] neg_hi:[0,1]
	v_exp_f32_e32 v174, v42
	v_exp_f32_e32 v175, v43
	v_pk_add_f32 v[24:25], v[24:25], v[172:173]
	v_pk_add_f32 v[32:33], v[32:33], v[0:1] op_sel_hi:[1,0] neg_lo:[0,1] neg_hi:[0,1]
	v_exp_f32_e32 v176, v36
	v_exp_f32_e32 v177, v37
	v_pk_add_f32 v[24:25], v[24:25], v[174:175]
	v_pk_add_f32 v[34:35], v[34:35], v[0:1] op_sel_hi:[1,0] neg_lo:[0,1] neg_hi:[0,1]
	v_exp_f32_e32 v178, v38
	v_exp_f32_e32 v179, v39
	v_pk_add_f32 v[24:25], v[24:25], v[176:177]
	v_pk_add_f32 v[28:29], v[28:29], v[0:1] op_sel_hi:[1,0] neg_lo:[0,1] neg_hi:[0,1]
	v_exp_f32_e32 v180, v32
	v_exp_f32_e32 v181, v33
	v_pk_add_f32 v[24:25], v[24:25], v[178:179]
	v_pk_add_f32 v[30:31], v[30:31], v[0:1] op_sel_hi:[1,0] neg_lo:[0,1] neg_hi:[0,1]
	v_exp_f32_e32 v182, v34
	v_exp_f32_e32 v183, v35
	v_pk_add_f32 v[24:25], v[24:25], v[180:181]
	v_pk_add_f32 v[20:21], v[20:21], v[0:1] op_sel_hi:[1,0] neg_lo:[0,1] neg_hi:[0,1]
	v_exp_f32_e32 v184, v28
	v_exp_f32_e32 v185, v29
	v_pk_add_f32 v[24:25], v[24:25], v[182:183]
	v_pk_add_f32 v[22:23], v[22:23], v[0:1] op_sel_hi:[1,0] neg_lo:[0,1] neg_hi:[0,1]
	v_exp_f32_e32 v226, v30
	v_exp_f32_e32 v227, v31
	v_pk_add_f32 v[24:25], v[24:25], v[184:185]
	v_exp_f32_e32 v228, v20
	v_exp_f32_e32 v229, v21
	v_pk_add_f32 v[24:25], v[24:25], v[226:227]
	v_exp_f32_e32 v230, v22
	v_exp_f32_e32 v231, v23
	v_pk_add_f32 v[24:25], v[24:25], v[228:229]
	v_pk_add_f32 v[24:25], v[24:25], v[230:231]
	v_lshl_add_u32 v32, vcc_hi, 1, v127
	v_lshl_add_u32 v48, s35, 1, v127
	v_add_f32_e32 v205, v24, v25
	ds_read_b128 v[20:23], v32
	ds_read_b128 v[24:27], v32 offset:16640
	ds_read_b128 v[28:31], v32 offset:33280
	ds_read_b128 v[32:35], v32 offset:49920
	ds_read_b128 v[36:39], v48
	ds_read_b128 v[40:43], v48 offset:16640
	ds_read_b128 v[44:47], v48 offset:33280
	ds_read_b128 v[48:51], v48 offset:49920
	v_mov_b32_e32 v206, v205
	s_nop 1
	v_permlane16_swap_b32_e32 v205, v206
	v_add_f32_e32 v205, v205, v206
	v_mov_b32_e32 v206, v205
	s_nop 1
	v_permlane32_swap_b32_e32 v205, v206
	v_cvt_pk_bf16_f32 v52, v52, v53
	v_cvt_pk_bf16_f32 v53, v54, v55
	v_cvt_pk_bf16_f32 v54, v164, v165
	v_cvt_pk_bf16_f32 v55, v166, v167
	s_setprio 1
	s_waitcnt lgkmcnt(7)
	v_mfma_f32_16x16x32_bf16 v[20:23], v[20:23], v[52:55], 0
	s_setprio 0
	s_setprio 1
	s_waitcnt lgkmcnt(6)
	v_mfma_f32_16x16x32_bf16 v[24:27], v[24:27], v[52:55], 0
	s_setprio 0
	s_setprio 1
	s_waitcnt lgkmcnt(5)
	v_mfma_f32_16x16x32_bf16 v[28:31], v[28:31], v[52:55], 0
	s_setprio 0
	s_setprio 1
	s_waitcnt lgkmcnt(4)
	v_mfma_f32_16x16x32_bf16 v[32:35], v[32:35], v[52:55], 0
	s_setprio 0
	v_cvt_pk_bf16_f32 v52, v168, v169
	v_cvt_pk_bf16_f32 v53, v170, v171
	v_cvt_pk_bf16_f32 v54, v172, v173
	v_cvt_pk_bf16_f32 v55, v174, v175
	s_setprio 1
	s_waitcnt lgkmcnt(3)
	v_mfma_f32_16x16x32_bf16 v[20:23], v[36:39], v[52:55], v[20:23]
	s_setprio 0
	s_setprio 1
	s_waitcnt lgkmcnt(2)
	v_mfma_f32_16x16x32_bf16 v[24:27], v[40:43], v[52:55], v[24:27]
	s_setprio 0
	s_setprio 1
	s_waitcnt lgkmcnt(1)
	v_mfma_f32_16x16x32_bf16 v[28:31], v[44:47], v[52:55], v[28:31]
	s_setprio 0
	s_setprio 1
	s_waitcnt lgkmcnt(0)
	v_mfma_f32_16x16x32_bf16 v[32:35], v[48:51], v[52:55], v[32:35]
	s_setprio 0
	v_lshl_add_u32 v48, vcc_lo, 1, v127
	v_lshl_add_u32 v172, s10, 1, v127
	ds_read_b128 v[36:39], v48
	ds_read_b128 v[40:43], v48 offset:16640
	ds_read_b128 v[44:47], v48 offset:33280
	ds_read_b128 v[48:51], v48 offset:49920
	ds_read_b128 v[52:55], v172
	ds_read_b128 v[164:167], v172 offset:16640
	ds_read_b128 v[168:171], v172 offset:33280
	ds_read_b128 v[172:175], v172 offset:49920
	v_cvt_pk_bf16_f32 v176, v176, v177
	v_cvt_pk_bf16_f32 v177, v178, v179
	v_cvt_pk_bf16_f32 v178, v180, v181
	v_cvt_pk_bf16_f32 v179, v182, v183
	s_setprio 1
	s_waitcnt lgkmcnt(7)
	v_mfma_f32_16x16x32_bf16 v[20:23], v[36:39], v[176:179], v[20:23]
	s_setprio 0
	s_setprio 1
	s_waitcnt lgkmcnt(6)
	v_mfma_f32_16x16x32_bf16 v[24:27], v[40:43], v[176:179], v[24:27]
	s_setprio 0
	s_setprio 1
	s_waitcnt lgkmcnt(5)
	v_mfma_f32_16x16x32_bf16 v[36:39], v[44:47], v[176:179], v[28:31]
	s_setprio 0
	s_setprio 1
	s_waitcnt lgkmcnt(4)
	v_mfma_f32_16x16x32_bf16 v[40:43], v[48:51], v[176:179], v[32:35]
	s_setprio 0
	v_cvt_pk_bf16_f32 v44, v184, v185
	v_cvt_pk_bf16_f32 v45, v226, v227
	v_cvt_pk_bf16_f32 v46, v228, v229
	v_cvt_pk_bf16_f32 v47, v230, v231
	s_setprio 1
	s_waitcnt lgkmcnt(3)
	v_mfma_f32_16x16x32_bf16 v[32:35], v[52:55], v[44:47], v[20:23]
	s_setprio 0
	s_setprio 1
	s_waitcnt lgkmcnt(2)
	v_mfma_f32_16x16x32_bf16 v[28:31], v[164:167], v[44:47], v[24:27]
	s_setprio 0
	s_setprio 1
	s_waitcnt lgkmcnt(1)
	v_mfma_f32_16x16x32_bf16 v[24:27], v[168:171], v[44:47], v[36:39]
	s_setprio 0
	s_setprio 1
	s_waitcnt lgkmcnt(0)
	v_mfma_f32_16x16x32_bf16 v[20:23], v[172:175], v[44:47], v[40:43]
	s_setprio 0
	s_andn2_b64 vcc, exec, s[80:81]
	v_add_f32_e32 v38, v205, v206
	s_cbranch_vccnz .LBB0_720
	v_cvt_pk_f16_f32 v36, v32, v33
	v_cvt_pk_f16_f32 v37, v34, v35
	ds_write2st64_b32 v128, v36, v37 offset0:2 offset1:3
	v_cvt_pk_f16_f32 v36, v28, v29
	v_cvt_pk_f16_f32 v37, v30, v31
	ds_write2st64_b32 v128, v36, v37 offset0:4 offset1:5
	v_cvt_pk_f16_f32 v36, v24, v25
	v_cvt_pk_f16_f32 v37, v26, v27
	ds_write2st64_b32 v128, v36, v37 offset0:6 offset1:7
	v_cvt_pk_f16_f32 v36, v20, v21
	v_cvt_pk_f16_f32 v37, v22, v23
	ds_write2st64_b32 v128, v0, v38 offset1:1
	ds_write2st64_b32 v128, v36, v37 offset0:8 offset1:9
